# GEMM phase prologues: all seven cold-start DMA stages issued before the first wait+barrier (one cold round trip instead of two) in all four GEMM phases
# speedup vs baseline: 1.0104x; 1.0104x over previous
.LBB0_111:
	v_readlane_b32 s10, v250, 21
	s_and_b32 s16, s1, 3
	v_readlane_b32 s11, v250, 22
	s_lshl_b32 s71, s0, 6
	s_lshl_b32 s15, s0, 13
	s_lshl_b32 s17, s16, 12
	s_lshl_b64 s[10:11], s[10:11], 16
	v_readlane_b32 s12, v251, 20
	v_readlane_b32 s20, v253, 35
	s_add_u32 s10, s12, s10
	v_readlane_b32 s12, v251, 21
	v_mov_b32_e32 v145, v1
	v_readlane_b32 s21, v253, 36
	s_addc_u32 s11, s12, s11
	s_add_i32 m0, s67, 0x18000
	v_lshl_add_u64 v[2:3], v[2:3], 0, s[30:31]
	v_lshl_add_u64 v[12:13], s[20:21], 0, v[144:145]
	v_mov_b32_e32 v141, v1
	global_load_lds_dwordx4 v[2:3], off
	v_lshl_add_u64 v[2:3], v[4:5], 0, s[30:31]
	s_add_i32 m0, s67, 0x1a000
	s_add_i32 s72, s67, 0x8000
	s_add_i32 s73, s67, 0xa000
	v_lshl_add_u64 v[14:15], s[20:21], 0, v[140:141]
	global_load_lds_dwordx4 v[2:3], off
	v_lshl_add_u64 v[2:3], v[12:13], 0, s[30:31]
	s_mov_b32 m0, s72
	s_add_u32 s12, s2, 0x80080
	global_load_lds_dwordx4 v[2:3], off
	v_lshl_add_u64 v[2:3], v[14:15], 0, s[30:31]
	s_mov_b32 m0, s73
	s_addc_u32 s13, s3, 0
	global_load_lds_dwordx4 v[2:3], off
	s_add_i32 m0, s67, 0x1c000
	v_lshl_add_u64 v[2:3], s[12:13], 0, v[142:143]
	global_load_lds_dwordx4 v[2:3], off
	v_lshl_add_u64 v[2:3], s[12:13], 0, v[138:139]
	s_add_i32 m0, s67, 0x1e000
	v_and_b32_e32 v147, 15, v0
	global_load_lds_dwordx4 v[2:3], off
	s_waitcnt vmcnt(8)
	s_barrier
	v_bfe_u32 v0, v0, 4, 2
	v_or_b32_e32 v2, s71, v147
	v_lshlrev_b32_e32 v170, 6, v2
	v_lshlrev_b32_e32 v2, 4, v0
	s_movk_i32 s12, 0x3c0
	v_lshlrev_b32_e32 v5, 2, v147
	v_and_or_b32 v4, v170, s12, v2
	v_and_b32_e32 v12, 32, v5
	v_lshl_or_b32 v2, v147, 6, v2
	s_cmpk_lt_u32 s14, 0x100
	v_lshlrev_b32_e32 v3, 3, v0
	v_bitop3_b32 v171, v2, s17, v12 bitop3:0xde
	s_cselect_b64 s[12:13], -1, 0
	s_bfe_u32 s17, s14, 0x10006
	v_cmp_gt_u32_e32 vcc, 2, v0
	v_cmp_eq_u32_e64 s[38:39], 0, v0
	v_lshlrev_b32_e32 v0, 15, v0
	v_readlane_b32 s18, v251, 18
	v_lshl_or_b32 v0, s17, 17, v0
	v_readlane_b32 s19, v251, 19
	s_cmp_eq_u32 s17, 0
	v_bitop3_b32 v4, v4, s15, v12 bitop3:0xde
	v_lshl_add_u64 v[148:149], s[18:19], 0, v[0:1]
	v_lshlrev_b32_e32 v0, 15, v10
	s_cselect_b64 s[14:15], -1, 0
	s_lshl_b32 s0, s0, 8
	v_and_b32_e32 v0, 0xffff0000, v0
	s_add_i32 s0, s0, 0
	v_lshl_add_u32 v0, v9, 12, v0
	v_and_b32_e32 v2, 1, v10
	s_bfe_u32 s75, s1, 0x10001
	s_add_i32 s1, s0, 0x20040
	s_add_i32 s0, s0, 0x20240
	v_lshl_or_b32 v0, v2, 6, v0
	v_add_u32_e32 v172, s1, v5
	v_add_u32_e32 v173, s0, v5
	v_lshl_add_u32 v150, v11, 1, v0
	v_lshlrev_b32_e32 v0, 15, v6
	v_readlane_b32 s0, v253, 31
	v_and_b32_e32 v0, 0xffff0000, v0
	v_readlane_b32 s1, v253, 32
	s_waitcnt vmcnt(6)
	v_lshl_add_u32 v0, v7, 12, v0
	v_and_b32_e32 v2, 1, v6
	s_mov_b32 s35, s0
	v_readlane_b32 s0, v253, 29
	v_lshl_or_b32 v0, v2, 6, v0
	v_readlane_b32 s1, v253, 30
	s_mov_b32 s74, 0
	s_and_b64 s[14:15], s[14:15], vcc
	v_and_b32_e32 v146, 8, v3
	v_lshl_or_b32 v174, s16, 5, v3
	v_mov_b32_e32 v151, v1
	v_lshl_add_u32 v152, v8, 1, v0
	v_mov_b32_e32 v153, v1
	v_add_u32_e32 v175, 0, v4
	s_mov_b32 s42, s0
	s_mov_b64 s[0:1], s[20:21]
	s_barrier
	s_branch .LBB0_114

.LBB0_840:
	v_readlane_b32 s4, v250, 21
	v_readlane_b32 s5, v250, 22
	s_lshl_b64 s[4:5], s[4:5], 12
	v_readlane_b32 s44, v250, 10
	v_lshrrev_b32_e32 v18, 1, v12
	v_readlane_b32 s45, v250, 11
	s_add_u32 s4, s44, s4
	v_and_b32_e32 v18, 24, v18
	v_readlane_b32 s12, v253, 24
	s_addc_u32 s5, s45, s5
	v_and_b32_e32 v13, 15, v12
	v_lshlrev_b32_e32 v19, 1, v18
	v_lshlrev_b32_e32 v12, 2, v12
	s_lshl_b32 s3, s3, 5
	v_mov_b32_e32 v135, v1
	v_readlane_b32 s13, v253, 25
	v_lshl_or_b32 v146, s6, 6, v13
	v_lshl_or_b32 v13, v13, 6, v19
	s_lshl_b32 s6, s6, 13
	v_and_b32_e32 v12, 32, v12
	s_and_b32 s3, s3, 0x60
	s_add_i32 m0, s29, 0x18000
	v_lshl_add_u64 v[2:3], v[2:3], 0, s[30:31]
	v_lshl_add_u64 v[14:15], s[12:13], 0, v[134:135]
	v_mov_b32_e32 v133, v1
	v_bitop3_b32 v19, v13, s6, v12 bitop3:0xde
	s_lshl_b32 s6, s3, 7
	global_load_lds_dwordx4 v[2:3], off
	v_lshl_add_u64 v[2:3], v[4:5], 0, s[30:31]
	s_add_i32 m0, s29, 0x1a000
	s_add_i32 s41, s29, 0x8000
	s_add_i32 s42, s29, 0xa000
	v_lshl_add_u64 v[16:17], s[12:13], 0, v[132:133]
	v_bitop3_b32 v147, v13, s6, v12 bitop3:0xde
	global_load_lds_dwordx4 v[2:3], off
	v_lshl_add_u64 v[2:3], v[14:15], 0, s[30:31]
	s_mov_b32 m0, s41
	s_add_u32 s6, s16, 0x40080
	global_load_lds_dwordx4 v[2:3], off
	v_lshl_add_u64 v[2:3], v[16:17], 0, s[30:31]
	s_mov_b32 m0, s42
	s_addc_u32 s7, s17, 0
	global_load_lds_dwordx4 v[2:3], off
	s_add_i32 m0, s29, 0x1c000
	v_lshl_add_u64 v[2:3], s[6:7], 0, v[0:1]
	global_load_lds_dwordx4 v[2:3], off
	v_lshl_add_u64 v[2:3], s[6:7], 0, v[130:131]
	s_add_i32 m0, s29, 0x1e000
	s_cmpk_lt_u32 s2, 0x100
	global_load_lds_dwordx4 v[2:3], off
	s_waitcnt vmcnt(8)
	s_barrier
	v_lshlrev_b32_e32 v2, 14, v10
	v_and_b32_e32 v2, 0xffff8000, v2
	v_lshl_add_u32 v2, v9, 11, v2
	v_and_b32_e32 v3, 1, v10
	v_lshl_or_b32 v2, v3, 6, v2
	v_lshl_add_u32 v136, v11, 1, v2
	v_lshlrev_b32_e32 v2, 14, v6
	v_and_b32_e32 v2, 0xffff8000, v2
	s_waitcnt vmcnt(6)
	v_lshl_add_u32 v2, v7, 11, v2
	v_and_b32_e32 v3, 1, v6
	v_lshl_or_b32 v2, v3, 6, v2
	v_readlane_b32 s52, v253, 22
	s_cselect_b64 s[6:7], -1, 0
	v_or_b32_e32 v148, s3, v18
	v_mov_b32_e32 v137, v1
	v_lshl_add_u32 v138, v8, 1, v2
	v_mov_b32_e32 v139, v1
	s_mov_b32 s43, 0
	v_add_u32_e32 v149, 0, v19
	v_readlane_b32 s35, v253, 20
	v_readlane_b32 s44, v253, 19
	s_mov_b64 s[2:3], s[12:13]
	v_readlane_b32 s53, v253, 23
	v_readlane_b32 s46, v250, 12
	v_readlane_b32 s47, v250, 13
	v_readlane_b32 s48, v250, 14
	v_readlane_b32 s49, v250, 15
	v_readlane_b32 s50, v250, 16
	v_readlane_b32 s51, v250, 17
	s_barrier
	s_branch .LBB0_843

.LBB0_912:
	v_lshrrev_b32_e32 v18, 1, v9
	v_and_b32_e32 v18, 24, v18
	v_readlane_b32 s10, v253, 43
	v_and_b32_e32 v13, 15, v9
	v_lshlrev_b32_e32 v19, 1, v18
	v_lshlrev_b32_e32 v9, 2, v9
	s_lshl_b32 s3, s3, 5
	v_mov_b32_e32 v135, v1
	v_readlane_b32 s11, v253, 44
	v_lshl_or_b32 v150, s4, 6, v13
	v_lshl_or_b32 v13, v13, 6, v19
	s_lshl_b32 s4, s4, 13
	v_and_b32_e32 v9, 32, v9
	s_and_b32 s3, s3, 0x60
	s_add_i32 m0, s21, 0x18000
	v_lshl_add_u64 v[2:3], v[2:3], 0, s[30:31]
	v_lshl_add_u64 v[14:15], s[10:11], 0, v[134:135]
	v_mov_b32_e32 v133, v1
	v_bitop3_b32 v19, v13, s4, v9 bitop3:0xde
	s_lshl_b32 s4, s3, 7
	global_load_lds_dwordx4 v[2:3], off
	v_lshl_add_u64 v[2:3], v[4:5], 0, s[30:31]
	s_add_i32 m0, s21, 0x1a000
	s_add_i32 s37, s21, 0x8000
	s_add_i32 s44, s21, 0xa000
	v_lshl_add_u64 v[16:17], s[10:11], 0, v[132:133]
	v_bitop3_b32 v151, v13, s4, v9 bitop3:0xde
	global_load_lds_dwordx4 v[2:3], off
	v_lshl_add_u64 v[2:3], v[14:15], 0, s[30:31]
	s_mov_b32 m0, s37
	s_add_u32 s4, s14, 0x40080
	global_load_lds_dwordx4 v[2:3], off
	v_lshl_add_u64 v[2:3], v[16:17], 0, s[30:31]
	s_mov_b32 m0, s44
	s_addc_u32 s5, s15, 0
	global_load_lds_dwordx4 v[2:3], off
	s_add_i32 m0, s21, 0x1c000
	v_lshl_add_u64 v[2:3], s[4:5], 0, v[0:1]
	global_load_lds_dwordx4 v[2:3], off
	v_lshl_add_u64 v[2:3], s[4:5], 0, v[130:131]
	s_add_i32 m0, s21, 0x1e000
	s_cmpk_lt_u32 s2, 0x100
	global_load_lds_dwordx4 v[2:3], off
	s_waitcnt vmcnt(8)
	s_barrier
	v_lshlrev_b32_e32 v2, 14, v11
	v_and_b32_e32 v2, 0xffff8000, v2
	v_lshl_add_u32 v2, v10, 11, v2
	v_and_b32_e32 v3, 1, v11
	v_lshl_or_b32 v2, v3, 6, v2
	v_lshl_add_u32 v136, v12, 1, v2
	v_lshlrev_b32_e32 v2, 14, v6
	v_and_b32_e32 v2, 0xffff8000, v2
	v_lshl_add_u32 v2, v7, 11, v2
	v_and_b32_e32 v3, 1, v6
	s_waitcnt vmcnt(6)
	v_or_b32_e32 v159, s3, v18
	v_lshl_or_b32 v2, v3, 6, v2
	v_readlane_b32 s2, v253, 49
	v_lshl_add_u32 v138, v8, 1, v2
	v_mov_b32_e32 v2, 0
	v_readlane_b32 s3, v253, 50
	s_cselect_b64 s[4:5], -1, 0
	v_or_b32_e32 v152, 16, v150
	v_or_b32_e32 v153, 32, v150
	v_or_b32_e32 v154, 48, v150
	v_add_u32_e32 v155, 0x80, v150
	v_add_u32_e32 v156, 0x90, v150
	v_add_u32_e32 v157, 0xa0, v150
	v_add_u32_e32 v158, 0xb0, v150
	v_mov_b32_e32 v137, v1
	v_mov_b32_e32 v139, v1
	s_mov_b32 s47, 0
	v_add_u32_e32 v160, 0, v19
	v_readlane_b32 s35, v253, 28
	s_mov_b32 s42, s2
	s_mov_b64 s[2:3], s[10:11]
	s_mov_b32 s45, 0
	v_mov_b32_e32 v3, v2
	v_mov_b32_e32 v4, v2
	v_mov_b32_e32 v5, v2
	v_mov_b32_e32 v6, v2
	v_mov_b32_e32 v7, v2
	v_mov_b32_e32 v8, v2
	v_mov_b32_e32 v9, v2
	v_mov_b32_e32 v10, v2
	v_mov_b32_e32 v11, v2
	v_mov_b32_e32 v12, v2
	v_mov_b32_e32 v13, v2
	v_mov_b32_e32 v14, v2
	v_mov_b32_e32 v15, v2
	v_mov_b32_e32 v16, v2
	v_mov_b32_e32 v17, v2
	v_mov_b32_e32 v18, v2
	v_mov_b32_e32 v19, v2
	v_mov_b32_e32 v20, v2
	v_mov_b32_e32 v21, v2
	v_mov_b32_e32 v22, v2
	v_mov_b32_e32 v23, v2
	v_mov_b32_e32 v24, v2
	v_mov_b32_e32 v25, v2
	v_mov_b32_e32 v26, v2
	v_mov_b32_e32 v27, v2
	v_mov_b32_e32 v28, v2
	v_mov_b32_e32 v29, v2
	v_mov_b32_e32 v30, v2
	v_mov_b32_e32 v31, v2
	v_mov_b32_e32 v32, v2
	v_mov_b32_e32 v33, v2
	v_mov_b32_e32 v34, v2
	v_mov_b32_e32 v35, v2
	v_mov_b32_e32 v36, v2
	v_mov_b32_e32 v37, v2
	v_mov_b32_e32 v38, v2
	v_mov_b32_e32 v39, v2
	v_mov_b32_e32 v40, v2
	v_mov_b32_e32 v41, v2
	v_mov_b32_e32 v42, v2
	v_mov_b32_e32 v43, v2
	v_mov_b32_e32 v44, v2
	v_mov_b32_e32 v45, v2
	v_mov_b32_e32 v46, v2
	v_mov_b32_e32 v47, v2
	v_mov_b32_e32 v48, v2
	v_mov_b32_e32 v49, v2
	v_mov_b32_e32 v50, v2
	v_mov_b32_e32 v51, v2
	v_mov_b32_e32 v52, v2
	v_mov_b32_e32 v53, v2
	v_mov_b32_e32 v54, v2
	v_mov_b32_e32 v55, v2
	v_mov_b32_e32 v56, v2
	v_mov_b32_e32 v57, v2
	v_mov_b32_e32 v58, v2
	v_mov_b32_e32 v59, v2
	v_mov_b32_e32 v60, v2
	v_mov_b32_e32 v61, v2
	v_mov_b32_e32 v62, v2
	v_mov_b32_e32 v63, v2
	v_mov_b32_e32 v64, v2
	v_mov_b32_e32 v65, v2
	v_mov_b32_e32 v66, v2
	v_mov_b32_e32 v67, v2
	v_mov_b32_e32 v68, v2
	v_mov_b32_e32 v69, v2
	v_mov_b32_e32 v70, v2
	v_mov_b32_e32 v71, v2
	v_mov_b32_e32 v72, v2
	v_mov_b32_e32 v73, v2
	v_mov_b32_e32 v74, v2
	v_mov_b32_e32 v75, v2
	v_mov_b32_e32 v76, v2
	v_mov_b32_e32 v77, v2
	v_mov_b32_e32 v78, v2
	v_mov_b32_e32 v79, v2
	v_mov_b32_e32 v80, v2
	v_mov_b32_e32 v81, v2
	v_mov_b32_e32 v82, v2
	v_mov_b32_e32 v83, v2
	v_mov_b32_e32 v84, v2
	v_mov_b32_e32 v85, v2
	v_mov_b32_e32 v86, v2
	v_mov_b32_e32 v87, v2
	v_mov_b32_e32 v88, v2
	v_mov_b32_e32 v89, v2
	v_mov_b32_e32 v90, v2
	v_mov_b32_e32 v91, v2
	v_mov_b32_e32 v92, v2
	v_mov_b32_e32 v93, v2
	v_mov_b32_e32 v94, v2
	v_mov_b32_e32 v95, v2
	v_mov_b32_e32 v96, v2
	v_mov_b32_e32 v97, v2
	v_mov_b32_e32 v98, v2
	v_mov_b32_e32 v99, v2
	v_mov_b32_e32 v100, v2
	v_mov_b32_e32 v101, v2
	v_mov_b32_e32 v102, v2
	v_mov_b32_e32 v103, v2
	v_mov_b32_e32 v104, v2
	v_mov_b32_e32 v105, v2
	v_mov_b32_e32 v106, v2
	v_mov_b32_e32 v107, v2
	v_mov_b32_e32 v108, v2
	v_mov_b32_e32 v109, v2
	v_mov_b32_e32 v110, v2
	v_mov_b32_e32 v111, v2
	v_mov_b32_e32 v112, v2
	v_mov_b32_e32 v113, v2
	v_mov_b32_e32 v114, v2
	v_mov_b32_e32 v115, v2
	v_mov_b32_e32 v116, v2
	v_mov_b32_e32 v117, v2
	v_mov_b32_e32 v118, v2
	v_mov_b32_e32 v119, v2
	v_mov_b32_e32 v120, v2
	v_mov_b32_e32 v121, v2
	v_mov_b32_e32 v122, v2
	v_mov_b32_e32 v123, v2
	v_mov_b32_e32 v124, v2
	v_mov_b32_e32 v125, v2
	v_mov_b32_e32 v126, v2
	v_mov_b32_e32 v127, v2
	v_mov_b32_e32 v128, v2
	v_mov_b32_e32 v129, v2
	s_barrier
	s_branch .LBB0_915

.LBB0_1050:
	v_readlane_b32 s6, v254, 32
	v_readlane_b32 s7, v254, 33
	v_readlane_b32 s8, v253, 10
	s_and_b64 s[6:7], s[6:7], exec
	v_readlane_b32 s9, v253, 11
	v_readlane_b32 s14, v253, 56
	v_readlane_b32 s10, v253, 12
	s_cselect_b32 s7, s9, s21
	s_cselect_b32 s6, s8, s20
	v_bfe_u32 v18, v12, 4, 2
	s_lshl_b32 s1, s1, 5
	v_mov_b32_e32 v135, v1
	v_readlane_b32 s15, v253, 57
	v_and_b32_e32 v13, 15, v12
	v_lshlrev_b32_e32 v19, 4, v18
	v_lshlrev_b32_e32 v12, 2, v12
	s_and_b32 s10, s1, 0x60
	s_add_i32 m0, s37, 0x18000
	v_lshl_add_u64 v[2:3], v[2:3], 0, s[30:31]
	v_lshl_add_u64 v[14:15], s[14:15], 0, v[134:135]
	v_mov_b32_e32 v133, v1
	v_lshl_or_b32 v152, s2, 6, v13
	v_lshl_or_b32 v13, v13, 6, v19
	s_lshl_b32 s2, s2, 13
	v_and_b32_e32 v12, 32, v12
	s_lshl_b32 s1, s10, 7
	global_load_lds_dwordx4 v[2:3], off
	v_lshl_add_u64 v[2:3], v[4:5], 0, s[30:31]
	s_add_i32 m0, s37, 0x1a000
	s_add_i32 s45, s37, 0x8000
	s_add_i32 s46, s37, 0xa000
	v_lshl_add_u64 v[16:17], s[14:15], 0, v[132:133]
	v_bitop3_b32 v19, v13, s2, v12 bitop3:0xde
	global_load_lds_dwordx4 v[2:3], off
	v_lshl_add_u64 v[2:3], v[14:15], 0, s[30:31]
	s_mov_b32 m0, s45
	s_add_u32 s2, s18, 0x80080
	global_load_lds_dwordx4 v[2:3], off
	v_lshl_add_u64 v[2:3], v[16:17], 0, s[30:31]
	s_mov_b32 m0, s46
	s_addc_u32 s3, s19, 0
	global_load_lds_dwordx4 v[2:3], off
	s_add_i32 m0, s37, 0x1c000
	v_lshl_add_u64 v[2:3], s[2:3], 0, v[0:1]
	global_load_lds_dwordx4 v[2:3], off
	v_lshl_add_u64 v[2:3], s[2:3], 0, v[130:131]
	s_add_i32 m0, s37, 0x1e000
	v_readlane_b32 s2, v253, 49
	global_load_lds_dwordx4 v[2:3], off
	s_waitcnt vmcnt(8)
	s_barrier
	v_lshlrev_b32_e32 v2, 15, v10
	v_and_b32_e32 v2, 0xffff0000, v2
	v_lshl_add_u32 v2, v9, 12, v2
	v_and_b32_e32 v3, 1, v10
	v_lshl_or_b32 v2, v3, 6, v2
	v_lshl_add_u32 v136, v11, 1, v2
	v_lshlrev_b32_e32 v2, 15, v6
	v_and_b32_e32 v2, 0xffff0000, v2
	s_waitcnt vmcnt(6)
	v_lshl_add_u32 v2, v7, 12, v2
	v_and_b32_e32 v3, 1, v6
	s_cmpk_lt_u32 s0, 0x100
	v_lshl_or_b32 v2, v3, 6, v2
	v_readlane_b32 s3, v253, 50
	v_bitop3_b32 v153, v13, s1, v12 bitop3:0xde
	s_cselect_b64 s[8:9], -1, 0
	s_mov_b32 s47, 0
	v_cmp_eq_u32_e64 s[0:1], 0, v18
	v_lshl_or_b32 v154, v18, 3, s10
	v_mov_b32_e32 v137, v1
	v_lshl_add_u32 v138, v8, 1, v2
	v_mov_b32_e32 v139, v1
	v_add_u32_e32 v155, 0, v19
	v_readlane_b32 s35, v253, 28
	s_mov_b32 s40, s2
	s_mov_b64 s[2:3], s[14:15]
	v_readlane_b32 s11, v253, 13
	s_barrier
	s_branch .LBB0_1053
